# phase-0 adaLN item: burst of 8 cache-warming loads covering the wave's w_ada slice before the dot-product loop
# baseline (speedup 1.0000x reference)
; DI float sigmoidf_(float x) { return frcp(1.0f + fexp2(-x * LOG2E)); }
; DI void phase_prep(KargPtr p, unsigned char* smem) {
;     ...
;             const int mi = item - NW; const int l = mi / 96, c0 = (mi % 96) * 64;
;             float* cond = fs;
;             float* red = fs + 8192;
;             for (int e = tid; e < 8192; e += 256) { const float cv = p->c[e]; cond[e] = cv * sigmoidf_(cv); }
;             __syncthreads();
;             const int tx = tid & 63, ty = tid >> 6;
;             float a0 = 0, a1 = 0, a2 = 0, a3 = 0, a4 = 0, a5 = 0, a6 = 0, a7 = 0;
;             const float* wsrc = p->w_ada + (size_t)l * 1024 * 6144 + c0 + tx;
; #pragma unroll 8
;             for (int k = ty * 256; k < ty * 256 + 256; ++k) {
;                 const float wv = wsrc[(size_t)k * 6144];
;                 a0 += cond[k] * wv; a1 += cond[1024 + k] * wv; a2 += cond[2048 + k] * wv; a3 += cond[3072 + k] * wv;
;                 a4 += cond[4096 + k] * wv; a5 += cond[5120 + k] * wv; a6 += cond[6144 + k] * wv; a7 += cond[7168 + k] * wv;
;             }
.LBB0_20:
	s_or_b64 exec, exec, s[8:9]
	s_add_i32 s12, s2, 0xffffedd8
	s_cmpk_gt_u32 s12, 0x5f
	s_cselect_b64 s[8:9], -1, 0
	s_add_i32 s22, s2, 0xffffed78
	s_waitcnt lgkmcnt(0)
	s_barrier
	s_load_dwordx2 s[20:21], s[10:11], 0x20
	s_cmpk_lt_u32 s12, 0x60
	s_cselect_b32 s12, s12, s22
	s_lshl_b32 s12, s12, 6
	s_and_b64 s[22:23], s[8:9], exec
	s_cselect_b32 s22, 0x1800000, 0
	s_waitcnt lgkmcnt(0)
	v_lshl_add_u64 v[2:3], s[20:21], 0, v[32:33]
	s_lshl_b64 s[20:21], s[12:13], 2
	s_add_u32 s22, s22, s20
	s_addc_u32 s23, 0, s21
	v_mov_b32_e32 v36, 0
	v_lshl_add_u64 v[34:35], v[2:3], 0, s[22:23]
	s_mov_b64 s[22:23], 0
	v_mov_b32_e32 v24, v23
	v_mov_b32_e32 v37, v36
	v_mov_b32_e32 v38, v36
	v_mov_b32_e32 v39, v36
	v_mov_b32_e32 v40, v36
	v_mov_b32_e32 v41, v36
	v_mov_b32_e32 v42, v36
	v_mov_b32_e32 v43, v36
	v_and_b32_e32 v110, 63, v199
	v_mul_u32_u24_e32 v110, 0x5ffc, v110
	v_mov_b32_e32 v111, 0
	v_lshl_add_u64 v[110:111], v[34:35], 0, v[110:111]
	global_load_dword v112, v[110:111], off
	global_load_dword v113, v[110:111], off offset:128
	v_add_co_u32_e32 v110, vcc, 0x180000, v110
	s_nop 1
	v_addc_co_u32_e32 v111, vcc, 0, v111, vcc
	global_load_dword v114, v[110:111], off
	global_load_dword v115, v[110:111], off offset:128
	v_add_co_u32_e32 v110, vcc, 0x180000, v110
	s_nop 1
	v_addc_co_u32_e32 v111, vcc, 0, v111, vcc
	global_load_dword v116, v[110:111], off
	global_load_dword v117, v[110:111], off offset:128
	v_add_co_u32_e32 v110, vcc, 0x180000, v110
	s_nop 1
	v_addc_co_u32_e32 v111, vcc, 0, v111, vcc
	global_load_dword v118, v[110:111], off
	global_load_dword v119, v[110:111], off offset:128
